# speedup vs baseline: 1.0206x; 1.0012x over previous
; __device__ __forceinline__ void scan_phase(const Params& p, char* shmc, int tid, int wv) {
;     ...
;   if (type) { w0 = WN_g + (long)h * 256 * 16384 + lt * 16; stw = 16384;
;               q0 = QP_g + (long)h * 256 * 16384 + lt * 16; stq = 16384; qrs = 4096; }
;   else      { q0 = QP_g + (((long)(lt >> 4)) * 1024 + h * 128) * 2 + (lt & 15) * 16; stq = 64 * 2048; qrs = 16 * 2048;
;               w0 = q0; stw = stq; }
;   const char* k0 = KD_g + (long)h * 256 * 16384 + lt * 16;
;   const char* p0 = PP_g + (long)h * 256 * 8192 + lt * 16;
;   const char* d0 = DD_g + (long)h * 256 * 512 + (lt & 31) * 16;
;   const int d_ = sl * 16 + r;
;   const char* su = type ? (UT_g + (long)h * 256 * 16384 + d_ * 128 + (4 * quad) * 2)
;                         : (UT_g + ((((long)(d_ >> 1)) * 1024 + h * 128 + (d_ & 1) * 64 + 4 * quad) * 2));
;   const long stu = type ? 16384 : 64 * 2048;
;   const int wrs = type ? 4096 : qrs;
;   const int ud_ = sl * 16 + ((lt & 127) >> 3);
;   const char* u0_ = type ? (UT_g + (long)h * 256 * 16384 + ud_ * 128 + (lt & 7) * 16)
;                          : (UT_g + (((long)(ud_ >> 1)) * 1024 + h * 128) * 2 + (ud_ & 1) * 128 + (lt & 7) * 16);
;     ...
;   } else if (wv == 1) {
;     for (int n = 0; n < 257; ++n) __builtin_amdgcn_s_barrier();
.LBB0_399:
	s_andn2_b64 vcc, exec, s[10:11]
	s_cbranch_vccnz .LBB0_402
	s_movk_i32 s7, 0x101
	v_mov_b64_e32 v[0:1], s[62:63]
	flat_load_dwordx2 v[0:1], v[0:1] offset:136
	v_mbcnt_lo_u32_b32 v2, -1, 0
	v_mbcnt_hi_u32_b32 v2, -1, v2
	v_lshrrev_b32_e32 v3, 4, v2
	v_and_b32_e32 v4, 15, v2
	s_lshr_b32 s10, s2, 4
	s_bfe_u32 s11, s2, 0x30001
	s_and_b32 s14, s2, 1
	v_lshl_add_u32 v4, s10, 4, v4
	s_cmp_eq_u32 s14, 0
	s_mov_b32 s15, 0x44018121
	s_cmov_b32 s15, 0x4a020161
	v_mov_b32_e32 v10, s15
	s_movk_i32 s15, 0x50
	s_cmov_b32 s15, 0x60
	v_mov_b32_e32 v11, s15
	v_mul_u32_u24_e32 v7, 10, v3
	v_lshrrev_b64 v[8:9], v7, v[10:11]
	v_and_b32_e32 v8, 0x3ff, v8
	v_lshlrev_b32_e32 v8, 20, v8
	v_lshlrev_b32_e32 v5, 7, v4
	v_mov_b32_e32 v6, 0x4000
	s_lshl_b32 s15, s11, 22
	v_mov_b32_e32 v9, s15
	v_and_b32_e32 v10, 7, v2
	v_lshl_add_u32 v10, s10, 3, v10
	v_lshlrev_b32_e32 v10, 7, v10
	s_lshl_b32 s15, s11, 21
	s_cmp_eq_u32 s14, 0
	s_cbranch_scc1 .Lsp_t0
	v_add_u32_e32 v11, 0x19100000, v10
	v_add_u32_e32 v11, s15, v11
	v_mov_b32_e32 v12, 0x2000
	s_branch .Lsp_go
.Lsp_t0:
	v_cmp_eq_u32_e32 vcc, 3, v3
	v_mov_b32_e32 v11, 0x2000
	v_mov_b32_e32 v12, s15
	s_nop 1
	v_cndmask_b32_e32 v5, v5, v10, vcc
	v_cndmask_b32_e32 v6, v6, v11, vcc
	v_cndmask_b32_e32 v9, v9, v12, vcc
	v_add_u32_e32 v11, -1, v3
	v_cmp_gt_u32_e32 vcc, 2, v11
	v_lshrrev_b32_e32 v11, 1, v4
	v_lshlrev_b32_e32 v11, 11, v11
	v_and_b32_e32 v12, 1, v4
	v_lshl_or_b32 v11, v12, 7, v11
	v_cndmask_b32_e32 v5, v5, v11, vcc
	v_mov_b32_e32 v11, 0x20000
	v_cndmask_b32_e32 v6, v6, v11, vcc
	s_lshl_b32 s15, s11, 8
	v_mov_b32_e32 v11, s15
	v_cndmask_b32_e32 v9, v9, v11, vcc
.Lsp_go:
	v_add3_u32 v5, v5, v8, v9
	s_cmp_eq_u32 s14, 0
	s_cbranch_scc0 .Lsp_go2
	v_mov_b32_e32 v11, v5
	v_mov_b32_e32 v12, v6
.Lsp_go2:
	s_waitcnt vmcnt(0) lgkmcnt(0)
	v_readfirstlane_b32 s12, v0
	v_readfirstlane_b32 s13, v1
	s_nop 4
.LBB0_401:
	s_add_i32 s7, s7, -1
	s_sub_i32 s15, 266, s7
	s_min_u32 s15, s15, 0xff
	v_mad_u32_u24 v9, v6, s15, v5
	v_mad_u32_u24 v10, v12, s15, v11
	global_load_dword v7, v9, s[12:13]
	global_load_dword v8, v10, s[12:13]
	s_cmp_eq_u32 s7, 0
	s_barrier
	s_cbranch_scc0 .LBB0_401
